# cmp_stage2 inner loop: LDS reads of step k+1 issued during step k (two register buffers), same arithmetic order
# baseline (speedup 1.0000x reference)
; __device__ __forceinline__ float bf_lo(unsigned u) { return __uint_as_float(u << 16); }
; __device__ __forceinline__ float bf_hi(unsigned u) { return __uint_as_float(u & 0xffff0000u); }
; __device__ __forceinline__ float gelu_tanh(float x) { const float u = 0.7978845608f * (x + 0.044715f * x * x * x); return x * rcpf_(1.f + ex2(-2.88539008f * u)); }
; __device__ __forceinline__ void cmp_stage2(const Ctx& C, int l) {
;     ...
;     for (int row = wi * NWAVES + C.wave; row < 4096; row += nwg2 * NWAVES) {
;         asm volatile("" ::: "memory");
;         const u32x2 hv = *((const u32x2*)(hid + (size_t)row * 256) + C.lane), hw = *((const u32x2*)(hid + (size_t)(row + 8192) * 256) + C.lane);
;         const f32x4 cbv = *((const f32x4*)cbias + C.lane);
;         const float h0 = gelu_tanh(bf_lo(hv.x) + bf_lo(hw.x) + cbv.x), h1 = gelu_tanh(bf_hi(hv.x) + bf_hi(hw.x) + cbv.y), h2 = gelu_tanh(bf_lo(hv.y) + bf_lo(hw.y) + cbv.z), h3 = gelu_tanh(bf_hi(hv.y) + bf_hi(hw.y) + cbv.w);
;         float acc = 0.f;
; #pragma unroll 4
;         for (int k = 0; k < 64; ++k) {
;             const float a0 = __int_as_float(__builtin_amdgcn_readlane(__float_as_int(h0), k)), a1 = __int_as_float(__builtin_amdgcn_readlane(__float_as_int(h1), k));
;             const float a2 = __int_as_float(__builtin_amdgcn_readlane(__float_as_int(h2), k)), a3 = __int_as_float(__builtin_amdgcn_readlane(__float_as_int(h3), k));
;             acc += a0 * ws2[(4 * k + 0) * 64 + d]; acc += a1 * ws2[(4 * k + 1) * 64 + d]; acc += a2 * ws2[(4 * k + 2) * 64 + d]; acc += a3 * ws2[(4 * k + 3) * 64 + d];
;         }
.LBB0_586:
	s_ashr_i32 s13, s12, 31
	s_lshl_b64 s[2:3], s[12:13], 9
	v_lshl_add_u64 v[12:13], v[8:9], 0, s[2:3]
	global_load_dwordx2 v[18:19], v[12:13], off
	v_add_co_u32_e32 v12, vcc, 0x400000, v12
	s_mov_b32 s2, 0
	s_nop 0
	v_addc_co_u32_e32 v13, vcc, 0, v13, vcc
	global_load_dwordx2 v[20:21], v[12:13], off
	s_nop 0
	global_load_dwordx4 v[12:15], v[10:11], off
	v_mov_b32_e32 v17, 0
	s_waitcnt vmcnt(2)
	v_lshlrev_b32_e32 v16, 16, v18
	v_and_b32_e32 v18, 0xffff0000, v18
	v_lshlrev_b32_e32 v22, 16, v19
	v_and_b32_e32 v19, 0xffff0000, v19
	s_waitcnt vmcnt(1)
	v_lshlrev_b32_e32 v23, 16, v20
	v_and_b32_e32 v20, 0xffff0000, v20
	v_lshlrev_b32_e32 v24, 16, v21
	v_and_b32_e32 v21, 0xffff0000, v21
	v_add_f32_e32 v16, v16, v23
	v_add_f32_e32 v18, v18, v20
	v_add_f32_e32 v20, v22, v24
	v_add_f32_e32 v19, v19, v21
	s_waitcnt vmcnt(0)
	v_add_f32_e32 v12, v12, v16
	v_add_f32_e32 v13, v13, v18
	v_add_f32_e32 v14, v14, v20
	v_add_f32_e32 v15, v15, v19
	v_mul_f32_e32 v16, 0x3d372713, v12
	v_mul_f32_e32 v18, 0x3d372713, v13
	v_mul_f32_e32 v19, 0x3d372713, v14
	v_mul_f32_e32 v20, 0x3d372713, v15
	v_mul_f32_e32 v16, v12, v16
	v_mul_f32_e32 v18, v13, v18
	v_mul_f32_e32 v19, v14, v19
	v_mul_f32_e32 v20, v15, v20
	v_fma_f32 v16, v12, v16, v12
	v_fma_f32 v18, v13, v18, v13
	v_fma_f32 v19, v14, v19, v14
	v_fma_f32 v20, v15, v20, v15
	v_mul_f32_e32 v16, 0x3f4c422a, v16
	v_mul_f32_e32 v18, 0x3f4c422a, v18
	v_mul_f32_e32 v19, 0x3f4c422a, v19
	v_mul_f32_e32 v20, 0x3f4c422a, v20
	v_mul_f32_e32 v16, 0xc038aa3b, v16
	v_mul_f32_e32 v18, 0xc038aa3b, v18
	v_mul_f32_e32 v19, 0xc038aa3b, v19
	v_mul_f32_e32 v20, 0xc038aa3b, v20
	v_exp_f32_e32 v16, v16
	v_exp_f32_e32 v18, v18
	v_exp_f32_e32 v19, v19
	v_exp_f32_e32 v20, v20
	v_add_f32_e32 v16, 1.0, v16
	v_add_f32_e32 v18, 1.0, v18
	v_add_f32_e32 v19, 1.0, v19
	v_add_f32_e32 v20, 1.0, v20
	v_rcp_f32_e32 v16, v16
	v_rcp_f32_e32 v18, v18
	v_rcp_f32_e32 v19, v19
	v_rcp_f32_e32 v20, v20
	v_mul_f32_e32 v12, v12, v16
	v_mul_f32_e32 v13, v13, v18
	v_mul_f32_e32 v14, v14, v19
	v_mul_f32_e32 v15, v15, v20
	v_mov_b32_e32 v16, v0
	ds_read_b32 v18, v16
	ds_read2st64_b32 v[20:21], v16 offset0:1 offset1:2
	ds_read_b32 v19, v16 offset:768
.LBB0_587:
	ds_read_b32 v22, v16 offset:1024
	ds_read2st64_b32 v[24:25], v16 offset0:5 offset1:6
	ds_read_b32 v23, v16 offset:1792
	v_readlane_b32 s10, v12, s2
	v_readlane_b32 s8, v13, s2
	v_readlane_b32 s9, v14, s2
	s_waitcnt lgkmcnt(3)
	v_fmac_f32_e32 v17, s10, v18
	v_pk_mul_f32 v[26:27], s[8:9], v[20:21]
	v_readlane_b32 s3, v15, s2
	v_add_f32_e32 v17, v17, v26
	v_add_f32_e32 v17, v17, v27
	v_fmac_f32_e32 v17, s3, v19
	ds_read_b32 v18, v16 offset:2048
	ds_read2st64_b32 v[20:21], v16 offset0:9 offset1:10
	ds_read_b32 v19, v16 offset:2816
	s_add_i32 s3, s2, 1
	v_readlane_b32 s10, v12, s3
	v_readlane_b32 s8, v13, s3
	v_readlane_b32 s9, v14, s3
	s_waitcnt lgkmcnt(3)
	v_fmac_f32_e32 v17, s10, v22
	v_pk_mul_f32 v[26:27], s[8:9], v[24:25]
	v_readlane_b32 s3, v15, s3
	v_add_f32_e32 v17, v17, v26
	v_add_f32_e32 v17, v17, v27
	v_fmac_f32_e32 v17, s3, v23
	ds_read_b32 v22, v16 offset:3072
	ds_read2st64_b32 v[24:25], v16 offset0:13 offset1:14
	ds_read_b32 v23, v16 offset:3840
	s_add_i32 s3, s2, 2
	v_readlane_b32 s10, v12, s3
	v_readlane_b32 s8, v13, s3
	v_readlane_b32 s9, v14, s3
	s_waitcnt lgkmcnt(3)
	v_fmac_f32_e32 v17, s10, v18
	v_pk_mul_f32 v[26:27], s[8:9], v[20:21]
	v_readlane_b32 s3, v15, s3
	v_add_f32_e32 v17, v17, v26
	v_add_f32_e32 v17, v17, v27
	v_fmac_f32_e32 v17, s3, v19
	ds_read_b32 v18, v16 offset:4096
	ds_read2st64_b32 v[20:21], v16 offset0:17 offset1:18
	ds_read_b32 v19, v16 offset:4864
	s_add_i32 s3, s2, 3
	v_readlane_b32 s10, v12, s3
	v_readlane_b32 s8, v13, s3
	v_readlane_b32 s9, v14, s3
	s_waitcnt lgkmcnt(3)
	v_fmac_f32_e32 v17, s10, v22
	v_pk_mul_f32 v[26:27], s[8:9], v[24:25]
	v_readlane_b32 s3, v15, s3
	v_add_f32_e32 v17, v17, v26
	v_add_f32_e32 v17, v17, v27
	v_fmac_f32_e32 v17, s3, v23
	s_add_i32 s2, s2, 4
	v_add_u32_e32 v16, 0x1000, v16
	s_cmp_eq_u32 s2, 64
	s_cbranch_scc0 .LBB0_587
	s_waitcnt lgkmcnt(0)
	s_ashr_i32 s2, s12, 3
	s_and_b32 s8, s2, 0xffffff80
	s_lshr_b32 s9, s12, 3
	s_mov_b64 s[2:3], -1
	s_and_b64 vcc, exec, s[4:5]
	s_cbranch_vccz .LBB0_590
	s_and_b32 s2, s9, 0x7e
	v_or_b32_e32 v12, s2, v3
	v_or_b32_e32 v12, s8, v12
	v_ashrrev_i32_e32 v13, 31, v12
	v_lshlrev_b64 v[12:13], 6, v[12:13]
	v_or_b32_e32 v12, v12, v2
	s_lshl_b32 s2, s12, 2
	v_and_or_b32 v12, s2, 32, v12
	s_mov_b64 s[2:3], 0
